# P0 pass: norm1 gain vector loaded once before the row loop (held in registers) instead of chunk-by-chunk reloads with full waits inside it
# baseline (speedup 1.0000x reference)
; #define LAS __attribute__((address_space(3)))
; __device__ __forceinline__ unsigned pk2(float lo, float hi) { return f2bf(lo) | (f2bf(hi) << 16); }
; __device__ __forceinline__ float wave_sum(float v) {
; #pragma unroll
;     for (int o = 1; o < 64; o <<= 1) v += __shfl_xor(v, o);
;     return v;
; }
; __device__ __forceinline__ void transpose_item(const float* W, int K, int N, bf16* WT, LAS float* scr, int item, int lane) {
;     const int nblk = N / 32, kb = item / nblk, nb = item % nblk, k0 = 64 * kb, n0 = 32 * nb;
; #pragma unroll 16
;     for (int i = 0; i < 32; ++i) { const int kk = 2 * i + (lane >> 5); scr[kk * 33 + (lane & 31)] = W[(size_t)(k0 + kk) * N + n0 + (lane & 31)]; }
;     asm volatile("s_waitcnt lgkmcnt(0)" ::: "memory");
;     const int c = lane & 7;
; #pragma unroll
;     for (int j = 0; j < 4; ++j) { const int n = (lane >> 3) + 8 * j; const LAS float* s = scr + (8 * c) * 33 + n;
;         v4u o; o.x = pk2(s[0 * 33], s[1 * 33]); o.y = pk2(s[2 * 33], s[3 * 33]); o.z = pk2(s[4 * 33], s[5 * 33]); o.w = pk2(s[6 * 33], s[7 * 33]);
;         *(v4u*)(WT + (size_t)(n0 + n) * K + k0 + 8 * c) = o; }
;     asm volatile("s_waitcnt lgkmcnt(0)" ::: "memory");
; }
; __device__ __forceinline__ float xg_row_bf16(const float* xrow, const float* g, bf16* orow, int lane) {
;     const f32x4* xr = (const f32x4*)xrow + lane; const f32x4* gr = (const f32x4*)g + lane;
;     f32x4 v[8]; float s = 0.f;
; #pragma unroll
;     for (int j = 0; j < 8; ++j) { v[j] = xr[64 * j]; s += (v[j].x * v[j].x + v[j].y * v[j].y) + (v[j].z * v[j].z + v[j].w * v[j].w); }
;     unsigned long long* o8 = (unsigned long long*)orow + lane;
; #pragma unroll
;     for (int j = 0; j < 8; ++j) { const f32x4 gg = gr[64 * j]; o8[64 * j] = (unsigned long long)pk2(v[j].x * gg.x, v[j].y * gg.y) | ((unsigned long long)pk2(v[j].z * gg.z, v[j].w * gg.w) << 32); }
;     return wave_sum(s);
; __global__ void __launch_bounds__(NWAVES * 64, 2) mega_fwd(Args args) {
;     ...
;         for (int m = gw; m < M; m += NGW) { const float* xr = m < M_P ? x_prompt + (size_t)m * DM : x_sample + (size_t)(m - M_P) * DM; const float sq = xg_row_bf16(xr, norm1_g, XN + (size_t)m * DM, lane); if (lane == 0) SSQ[m] = sq; }
.LBB0_31:
	s_or_b64 exec, exec, s[8:9]
	s_cmp_gt_i32 s66, 0x9fff
	s_cbranch_scc1 .LBB0_38
	v_mbcnt_lo_u32_b32 v1, -1, 0
	v_mbcnt_hi_u32_b32 v2, -1, v1
	v_and_b32_e32 v1, 64, v2
	v_add_u32_e32 v3, 64, v1
	v_xor_b32_e32 v1, 1, v2
	v_cmp_lt_i32_e32 vcc, v1, v3
	v_xor_b32_e32 v4, 2, v2
	v_ashrrev_i32_e32 v7, 31, v6
	v_cndmask_b32_e32 v1, v2, v1, vcc
	v_cmp_lt_i32_e32 vcc, v4, v3
	v_lshl_add_u64 v[8:9], v[6:7], 4, s[18:19]
	s_mov_b64 s[0:1], 0x1000
	v_cndmask_b32_e32 v4, v2, v4, vcc
	v_lshlrev_b32_e32 v22, 2, v4
	v_xor_b32_e32 v4, 4, v2
	v_cmp_lt_i32_e32 vcc, v4, v3
	v_lshl_add_u64 v[12:13], v[8:9], 0, s[0:1]
	s_mov_b64 s[0:1], 0x1400
	v_cndmask_b32_e32 v4, v2, v4, vcc
	v_lshlrev_b32_e32 v23, 2, v4
	v_xor_b32_e32 v4, 8, v2
	v_cmp_lt_i32_e32 vcc, v4, v3
	v_lshl_add_u64 v[14:15], v[8:9], 0, s[0:1]
	s_mov_b64 s[0:1], 0x1800
	v_cndmask_b32_e32 v4, v2, v4, vcc
	v_lshlrev_b32_e32 v24, 2, v4
	v_xor_b32_e32 v4, 16, v2
	v_cmp_lt_i32_e32 vcc, v4, v3
	v_lshl_add_u64 v[16:17], v[8:9], 0, s[0:1]
	s_mov_b64 s[0:1], 0x1c00
	v_cndmask_b32_e32 v4, v2, v4, vcc
	v_lshlrev_b32_e32 v25, 2, v4
	v_xor_b32_e32 v4, 32, v2
	s_ashr_i32 s67, s66, 31
	v_lshl_add_u64 v[18:19], v[8:9], 0, s[0:1]
	v_cmp_lt_i32_e32 vcc, v4, v3
	s_ashr_i32 s69, s68, 31
	s_lshl_b64 s[0:1], s[66:67], 13
	v_cndmask_b32_e32 v2, v2, v4, vcc
	s_add_u32 s10, s12, s0
	v_lshl_add_u64 v[10:11], v[6:7], 3, s[58:59]
	s_mov_b32 s9, 0
	v_lshlrev_b32_e32 v1, 2, v1
	v_lshlrev_b32_e32 v26, 2, v2
	v_cmp_eq_u32_e32 vcc, 0, v6
	s_addc_u32 s11, s13, s1
	s_lshl_b64 s[20:21], s[68:69], 13
	s_movk_i32 s3, 0x1000
	s_movk_i32 s33, 0x7fff
	s_waitcnt lgkmcnt(0)
	s_mov_b32 s46, 0xffff0000
	v_mov_b32_e32 v27, 0
	s_mov_b64 s[34:35], s[66:67]
	global_load_dwordx4 v[64:67], v[8:9], off
	global_load_dwordx4 v[68:71], v[8:9], off offset:1024
	global_load_dwordx4 v[72:75], v[8:9], off offset:2048
	global_load_dwordx4 v[76:79], v[8:9], off offset:3072
	global_load_dwordx4 v[80:83], v[12:13], off
	global_load_dwordx4 v[84:87], v[14:15], off
	global_load_dwordx4 v[88:91], v[16:17], off
	global_load_dwordx4 v[92:95], v[18:19], off
	s_branch .LBB0_34

; #define LAS __attribute__((address_space(3)))
; __device__ __forceinline__ unsigned f2bf(float f) { unsigned u = __builtin_bit_cast(unsigned, f); return (u + 0x7fffu + ((u >> 16) & 1u)) >> 16; }
; __device__ __forceinline__ unsigned pk2(float lo, float hi) { return f2bf(lo) | (f2bf(hi) << 16); }
; __device__ __forceinline__ float wave_sum(float v) {
; #pragma unroll
;     for (int o = 1; o < 64; o <<= 1) v += __shfl_xor(v, o);
;     return v;
; }
; __device__ __forceinline__ void transpose_item(const float* W, int K, int N, bf16* WT, LAS float* scr, int item, int lane) {
;     const int nblk = N / 32, kb = item / nblk, nb = item % nblk, k0 = 64 * kb, n0 = 32 * nb;
; #pragma unroll 16
;     for (int i = 0; i < 32; ++i) { const int kk = 2 * i + (lane >> 5); scr[kk * 33 + (lane & 31)] = W[(size_t)(k0 + kk) * N + n0 + (lane & 31)]; }
;     asm volatile("s_waitcnt lgkmcnt(0)" ::: "memory");
;     const int c = lane & 7;
; #pragma unroll
;     for (int j = 0; j < 4; ++j) { const int n = (lane >> 3) + 8 * j; const LAS float* s = scr + (8 * c) * 33 + n;
;         v4u o; o.x = pk2(s[0 * 33], s[1 * 33]); o.y = pk2(s[2 * 33], s[3 * 33]); o.z = pk2(s[4 * 33], s[5 * 33]); o.w = pk2(s[6 * 33], s[7 * 33]);
;         *(v4u*)(WT + (size_t)(n0 + n) * K + k0 + 8 * c) = o; }
;     asm volatile("s_waitcnt lgkmcnt(0)" ::: "memory");
; }
; __device__ __forceinline__ float xg_row_bf16(const float* xrow, const float* g, bf16* orow, int lane) {
;     const f32x4* xr = (const f32x4*)xrow + lane; const f32x4* gr = (const f32x4*)g + lane;
;     f32x4 v[8]; float s = 0.f;
; #pragma unroll
;     for (int j = 0; j < 8; ++j) { v[j] = xr[64 * j]; s += (v[j].x * v[j].x + v[j].y * v[j].y) + (v[j].z * v[j].z + v[j].w * v[j].w); }
;     unsigned long long* o8 = (unsigned long long*)orow + lane;
; #pragma unroll
;     for (int j = 0; j < 8; ++j) { const f32x4 gg = gr[64 * j]; o8[64 * j] = (unsigned long long)pk2(v[j].x * gg.x, v[j].y * gg.y) | ((unsigned long long)pk2(v[j].z * gg.z, v[j].w * gg.w) << 32); }
;     return wave_sum(s);
.LBB0_36:
	v_lshl_add_u64 v[2:3], v[6:7], 4, s[0:1]
	s_waitcnt lgkmcnt(0)
	global_load_dwordx4 v[32:35], v[2:3], off
	s_lshl_b64 s[48:49], s[42:43], 12
	global_load_dwordx4 v[36:39], v[2:3], off offset:1024
	global_load_dwordx4 v[40:43], v[2:3], off offset:2048
	global_load_dwordx4 v[44:47], v[2:3], off offset:3072
	v_add_co_u32_e64 v2, s[0:1], s3, v2
	v_lshl_add_u64 v[20:21], v[10:11], 0, s[48:49]
	s_nop 0
	v_addc_co_u32_e64 v3, s[0:1], 0, v3, s[0:1]
	global_load_dwordx4 v[48:51], v[2:3], off
	global_load_dwordx4 v[52:55], v[2:3], off offset:1024
	global_load_dwordx4 v[56:59], v[2:3], off offset:2048
	s_nop 0
	global_load_dwordx4 v[2:5], v[2:3], off offset:3072
	s_waitcnt vmcnt(7)
	v_mul_f32_e32 v28, v32, v64
	v_mul_f32_e32 v30, v34, v66
	v_mul_f32_e32 v29, v33, v65
	v_mul_f32_e32 v31, v35, v67
	v_bfe_u32 v60, v28, 16, 1
	v_bfe_u32 v62, v30, 16, 1
	v_bfe_u32 v61, v29, 16, 1
	v_bfe_u32 v63, v31, 16, 1
	v_add3_u32 v28, v28, v60, s33
	v_add3_u32 v30, v30, v62, s33
	v_add3_u32 v29, v29, v61, s33
	v_add3_u32 v31, v31, v63, s33
	v_lshrrev_b32_e32 v28, 16, v28
	v_lshrrev_b32_e32 v30, 16, v30
	v_and_or_b32 v28, v29, s46, v28
	v_and_or_b32 v29, v31, s46, v30
	global_store_dwordx2 v[20:21], v[28:29], off
	s_waitcnt vmcnt(7)
	v_mul_f32_e32 v28, v36, v68
	v_mul_f32_e32 v30, v38, v70
	v_mul_f32_e32 v29, v37, v69
	v_mul_f32_e32 v31, v39, v71
	v_bfe_u32 v60, v28, 16, 1
	v_bfe_u32 v62, v30, 16, 1
	v_bfe_u32 v61, v29, 16, 1
	v_bfe_u32 v63, v31, 16, 1
	v_add3_u32 v28, v28, v60, s33
	v_add3_u32 v30, v30, v62, s33
	v_add3_u32 v29, v29, v61, s33
	v_add3_u32 v31, v31, v63, s33
	v_lshrrev_b32_e32 v28, 16, v28
	v_lshrrev_b32_e32 v30, 16, v30
	v_and_or_b32 v28, v29, s46, v28
	v_and_or_b32 v29, v31, s46, v30
	global_store_dwordx2 v[20:21], v[28:29], off offset:512
	s_waitcnt vmcnt(7)
	v_mul_f32_e32 v28, v40, v72
	v_mul_f32_e32 v30, v42, v74
	v_mul_f32_e32 v29, v41, v73
	v_mul_f32_e32 v31, v43, v75
	v_bfe_u32 v60, v28, 16, 1
	v_bfe_u32 v62, v30, 16, 1
	v_bfe_u32 v61, v29, 16, 1
	v_bfe_u32 v63, v31, 16, 1
	v_add3_u32 v28, v28, v60, s33
	v_add3_u32 v30, v30, v62, s33
	v_add3_u32 v29, v29, v61, s33
	v_add3_u32 v31, v31, v63, s33
	v_lshrrev_b32_e32 v28, 16, v28
	v_lshrrev_b32_e32 v30, 16, v30
	v_and_or_b32 v28, v29, s46, v28
	v_and_or_b32 v29, v31, s46, v30
	global_store_dwordx2 v[20:21], v[28:29], off offset:1024
	s_waitcnt vmcnt(7)
	v_mul_f32_e32 v28, v44, v76
	v_mul_f32_e32 v30, v46, v78
	v_mul_f32_e32 v29, v45, v77
	v_mul_f32_e32 v31, v47, v79
	v_bfe_u32 v60, v28, 16, 1
	v_bfe_u32 v62, v30, 16, 1
	v_bfe_u32 v61, v29, 16, 1
	v_bfe_u32 v63, v31, 16, 1
	v_add3_u32 v28, v28, v60, s33
	v_add3_u32 v30, v30, v62, s33
	v_add3_u32 v29, v29, v61, s33
	v_add3_u32 v31, v31, v63, s33
	v_lshrrev_b32_e32 v28, 16, v28
	v_lshrrev_b32_e32 v30, 16, v30
	v_and_or_b32 v28, v29, s46, v28
	v_and_or_b32 v29, v31, s46, v30
	global_store_dwordx2 v[20:21], v[28:29], off offset:1536
	s_waitcnt vmcnt(7)
	v_mul_f32_e32 v28, v48, v80
	v_mul_f32_e32 v30, v50, v82
	v_mul_f32_e32 v29, v49, v81
	v_mul_f32_e32 v31, v51, v83
	v_bfe_u32 v60, v28, 16, 1
	v_bfe_u32 v62, v30, 16, 1
	v_bfe_u32 v61, v29, 16, 1
	v_bfe_u32 v63, v31, 16, 1
	v_add3_u32 v28, v28, v60, s33
	v_add3_u32 v30, v30, v62, s33
	v_add3_u32 v29, v29, v61, s33
	v_add3_u32 v31, v31, v63, s33
	v_lshrrev_b32_e32 v28, 16, v28
	v_lshrrev_b32_e32 v30, 16, v30
	v_and_or_b32 v28, v29, s46, v28
	v_and_or_b32 v29, v31, s46, v30
	global_store_dwordx2 v[20:21], v[28:29], off offset:2048
	s_waitcnt vmcnt(7)
	v_mul_f32_e32 v28, v52, v84
	v_mul_f32_e32 v30, v54, v86
	v_mul_f32_e32 v29, v53, v85
	v_mul_f32_e32 v31, v55, v87
	v_bfe_u32 v60, v28, 16, 1
	v_bfe_u32 v62, v30, 16, 1
	v_bfe_u32 v61, v29, 16, 1
	v_bfe_u32 v63, v31, 16, 1
	v_add3_u32 v28, v28, v60, s33
	v_add3_u32 v30, v30, v62, s33
	v_add3_u32 v29, v29, v61, s33
	v_add3_u32 v31, v31, v63, s33
	v_lshrrev_b32_e32 v28, 16, v28
	v_lshrrev_b32_e32 v30, 16, v30
	v_and_or_b32 v28, v29, s46, v28
	v_and_or_b32 v29, v31, s46, v30
	global_store_dwordx2 v[20:21], v[28:29], off offset:2560
	s_waitcnt vmcnt(7)
	v_mul_f32_e32 v28, v56, v88
	v_mul_f32_e32 v30, v58, v90
	v_mul_f32_e32 v29, v57, v89
	v_mul_f32_e32 v31, v59, v91
	v_bfe_u32 v60, v28, 16, 1
	v_bfe_u32 v62, v30, 16, 1
	v_bfe_u32 v61, v29, 16, 1
	v_bfe_u32 v63, v31, 16, 1
	v_add3_u32 v28, v28, v60, s33
	v_add3_u32 v30, v30, v62, s33
	v_add3_u32 v29, v29, v61, s33
	v_add3_u32 v31, v31, v63, s33
	v_lshrrev_b32_e32 v28, 16, v28
	v_lshrrev_b32_e32 v30, 16, v30
	v_and_or_b32 v28, v29, s46, v28
	v_and_or_b32 v29, v31, s46, v30
	global_store_dwordx2 v[20:21], v[28:29], off offset:3072
	s_waitcnt vmcnt(7)
	v_mul_f32_e32 v28, v33, v33
	v_mul_f32_e32 v29, v35, v35
	v_mul_f32_e32 v30, v37, v37
	v_mul_f32_e32 v31, v39, v39
	v_mul_f32_e32 v33, v41, v41
	v_mul_f32_e32 v35, v43, v43
	v_fmac_f32_e32 v29, v34, v34
	v_fmac_f32_e32 v30, v36, v36
	v_fmac_f32_e32 v31, v38, v38
	v_fmac_f32_e32 v28, v32, v32
	v_mul_f32_e32 v37, v45, v45
	v_mul_f32_e32 v39, v47, v47
	v_fmac_f32_e32 v33, v40, v40
	v_fmac_f32_e32 v35, v42, v42
	v_add_f32_e32 v30, v30, v31
	v_add_f32_e32 v28, v28, v29
	v_fmac_f32_e32 v37, v44, v44
	v_fmac_f32_e32 v39, v46, v46
	v_mul_f32_e32 v34, v49, v49
	v_mul_f32_e32 v36, v51, v51
	v_add_f32_e32 v31, v33, v35
	v_add_f32_e32 v28, v28, v30
	v_mul_f32_e32 v38, v53, v53
	v_mul_f32_e32 v40, v55, v55
	v_add_f32_e32 v32, v37, v39
	v_fmac_f32_e32 v34, v48, v48
	v_fmac_f32_e32 v36, v50, v50
	v_add_f32_e32 v28, v28, v31
	v_mul_f32_e32 v41, v57, v57
	v_mul_f32_e32 v42, v59, v59
	v_fmac_f32_e32 v38, v52, v52
	v_fmac_f32_e32 v40, v54, v54
	v_add_f32_e32 v29, v34, v36
	v_add_f32_e32 v28, v28, v32
	v_mul_f32_e32 v43, v3, v3
	v_mul_f32_e32 v44, v5, v5
	v_fmac_f32_e32 v41, v56, v56
	v_fmac_f32_e32 v42, v58, v58
	v_add_f32_e32 v33, v38, v40
	v_add_f32_e32 v28, v28, v29
	v_fmac_f32_e32 v43, v2, v2
	v_fmac_f32_e32 v44, v4, v4
	v_add_f32_e32 v34, v41, v42
	v_add_f32_e32 v28, v28, v33
	v_add_f32_e32 v35, v43, v44
	v_add_f32_e32 v28, v28, v34
	v_add_f32_e32 v28, v28, v35
	ds_bpermute_b32 v29, v1, v28
	s_waitcnt lgkmcnt(0)
	v_add_f32_e32 v28, v28, v29
	ds_bpermute_b32 v29, v22, v28
	s_waitcnt lgkmcnt(0)
	v_add_f32_e32 v28, v28, v29
	ds_bpermute_b32 v29, v23, v28
	s_waitcnt lgkmcnt(0)
	v_add_f32_e32 v28, v28, v29
	ds_bpermute_b32 v29, v24, v28
	s_waitcnt lgkmcnt(0)
	v_add_f32_e32 v28, v28, v29
	ds_bpermute_b32 v29, v25, v28
	s_waitcnt lgkmcnt(0)
	v_add_f32_e32 v28, v28, v29
	ds_bpermute_b32 v29, v26, v28
	s_waitcnt vmcnt(7)
	v_mul_f32_e32 v2, v2, v92
	v_mul_f32_e32 v4, v4, v94
	v_mul_f32_e32 v3, v3, v93
	v_mul_f32_e32 v5, v5, v95
	v_bfe_u32 v30, v2, 16, 1
	v_bfe_u32 v32, v4, 16, 1
	v_bfe_u32 v31, v3, 16, 1
	v_bfe_u32 v33, v5, 16, 1
	v_add3_u32 v2, v2, v30, s33
	v_add3_u32 v4, v4, v32, s33
	v_add3_u32 v3, v3, v31, s33
	v_add3_u32 v5, v5, v33, s33
	v_lshrrev_b32_e32 v2, 16, v2
	v_lshrrev_b32_e32 v4, 16, v4
	v_and_or_b32 v2, v3, s46, v2
	v_and_or_b32 v3, v5, s46, v4
	global_store_dwordx2 v[20:21], v[2:3], off offset:3584
	s_and_saveexec_b64 s[0:1], vcc
	s_cbranch_execz .LBB0_33
; __global__ void __launch_bounds__(NWAVES * 64, 2) mega_fwd(Args args) {
;     ...
;         for (int m = gw; m < M; m += NGW) { const float* xr = m < M_P ? x_prompt + (size_t)m * DM : x_sample + (size_t)(m - M_P) * DM; const float sq = xg_row_bf16(xr, norm1_g, XN + (size_t)m * DM, lane); if (lane == 0) SSQ[m] = sq; }
	s_lshl_b64 s[42:43], s[42:43], 2
	s_add_u32 s42, s30, s42
	s_addc_u32 s43, s31, s43
	s_waitcnt lgkmcnt(0)
	v_add_f32_e32 v2, v28, v29
	global_store_dword v27, v2, s[42:43]
	s_branch .LBB0_33
